# pre-pass: every block alternates HGRN and GLA units (kind = unit-round parity xor block parity) so both co-resident blocks no longer run the same load-heavy kind
# speedup vs baseline: 1.0119x; 1.0013x over previous
.Lpre_init:
	v_and_b32_e32 v140, 0x7f, v156
	v_lshlrev_b32_e32 v141, 1, v140
	v_lshlrev_b32_e32 v140, 2, v140
	v_and_b32_e32 v142, 63, v156
	v_lshlrev_b32_e32 v143, 1, v142
	v_lshlrev_b32_e32 v142, 2, v142
	v_lshlrev_b32_e32 v144, 2, v156
	v_lshrrev_b32_e32 v32, 6, v156
	s_nop 1
	v_readfirstlane_b32 s17, v32
	v_and_b32_e32 v146, 63, v156
	v_lshlrev_b32_e32 v146, 4, v146
	s_lshl_b32 s4, s17, 10
	s_add_u32 s4, s4, 0x400
	v_mov_b32_e32 v139, s4
	v_add_u32_e32 v147, s4, v146
	s_mov_b32 s10, 0x3fb8aa3b
	s_mov_b32 s11, 0xbfb8aa3b
	s_mov_b32 s12, 0x3f317218
	s_mov_b32 s13, 0x3d800000
	s_bfe_u32 s18, s88, 0x20001
	v_readlane_b32 s36, v253, 28
	v_readlane_b32 s37, v253, 29
	v_readlane_b32 s34, v253, 30
	v_readlane_b32 s35, v253, 31
	s_nop 3
	s_lshl_b32 s4, s18, 8
	s_add_u32 s36, s36, s4
	s_addc_u32 s37, s37, 0
	s_add_u32 s34, s34, s4
	s_addc_u32 s35, s35, 0
	s_nop 3
	global_load_dword v138, v142, s[34:35]
	global_load_dword v210, v142, s[36:37]
	global_load_dword v211, v142, s[36:37] offset:1024
	global_load_dword v212, v142, s[36:37] offset:2048
	global_load_dword v213, v142, s[36:37] offset:3072
	s_add_u32 s36, s36, 0x1000
	s_addc_u32 s37, s37, 0
	global_load_dword v214, v142, s[36:37]
	global_load_dword v215, v142, s[36:37] offset:1024
	global_load_dword v216, v142, s[36:37] offset:2048
	global_load_dword v217, v142, s[36:37] offset:3072
	s_add_u32 s36, s36, 0x1000
	s_addc_u32 s37, s37, 0
	global_load_dword v218, v142, s[36:37]
	global_load_dword v219, v142, s[36:37] offset:1024
	global_load_dword v220, v142, s[36:37] offset:2048
	global_load_dword v221, v142, s[36:37] offset:3072
	s_add_u32 s36, s36, 0x1000
	s_addc_u32 s37, s37, 0
	global_load_dword v128, v142, s[36:37]
	global_load_dword v129, v142, s[36:37] offset:1024
	global_load_dword v130, v142, s[36:37] offset:2048
	global_load_dword v131, v142, s[36:37] offset:3072
.Lpre_loop:
	s_lshr_b32 s4, s16, 9
	s_xor_b32 s4, s4, s88
	s_bitcmp1_b32 s4, 0
	s_cbranch_scc1 .Lpre_g_unit
	s_lshr_b32 s19, s16, 3
	s_lshr_b32 s4, s17, 1
	s_lshl_b32 s4, s4, 5
	s_mov_b32 s23, 1
	s_cmp_lt_u32 s19, 0x400
	s_cbranch_scc1 .Lpre_h_full
	s_sub_u32 s20, s19, 0x400
	s_lshl_b32 s20, s20, 5
	s_add_u32 s20, s20, 0x10000
	s_add_u32 s20, s20, s4
	s_cmp_lt_u32 s4, 32
	s_cbranch_scc1 .Lpre_h_go
	s_mov_b32 s23, 0
	v_mov_b32_e32 v145, 0
	s_branch .Lpre_h_exch

.Lpre_h_next:
	s_branch .Lpre_next

.Lpre_g_go:
	s_lshl_b32 s21, s20, 6
	s_add_u32 s22, s21, 0x28500000
	s_add_u32 s24, s94, s22
	s_addc_u32 s25, s95, 0
	s_lshl_b32 s21, s20, 9
	s_lshl_b32 s4, s18, 7
	s_add_u32 s21, s21, s4
	s_add_u32 s22, s21, 0x1c380000
	s_add_u32 s26, s94, s22
	s_addc_u32 s27, s95, 0
	s_mov_b64 s[28:29], s[26:27]
	s_add_u32 s22, s21, 0x2e5c0000
	s_add_u32 s30, s94, s22
	s_addc_u32 s31, s95, 0
	s_add_u32 s22, s21, 0x1e3c0000
	s_add_u32 s34, s94, s22
	s_addc_u32 s35, s95, 0
	global_load_dwordx4 v[44:47], v146, s[24:25]
	global_load_ushort v96, v143, s[34:35]
	global_load_ushort v97, v143, s[34:35] offset:512
	global_load_ushort v98, v143, s[34:35] offset:1024
	global_load_ushort v99, v143, s[34:35] offset:1536
	global_load_ushort v100, v143, s[34:35] offset:2048
	global_load_ushort v101, v143, s[34:35] offset:2560
	global_load_ushort v102, v143, s[34:35] offset:3072
	global_load_ushort v103, v143, s[34:35] offset:3584
	s_add_u32 s34, s34, 0x1000
	s_addc_u32 s35, s35, 0
	global_load_ushort v104, v143, s[34:35]
	global_load_ushort v105, v143, s[34:35] offset:512
	global_load_ushort v106, v143, s[34:35] offset:1024
	global_load_ushort v107, v143, s[34:35] offset:1536
	global_load_ushort v108, v143, s[34:35] offset:2048
	global_load_ushort v109, v143, s[34:35] offset:2560
	global_load_ushort v110, v143, s[34:35] offset:3072
	global_load_ushort v111, v143, s[34:35] offset:3584
	global_load_ushort v0, v143, s[26:27]
	global_load_ushort v1, v143, s[26:27] offset:512
	global_load_ushort v2, v143, s[26:27] offset:1024
	global_load_ushort v3, v143, s[26:27] offset:1536
	global_load_ushort v4, v143, s[26:27] offset:2048
	global_load_ushort v5, v143, s[26:27] offset:2560
	global_load_ushort v6, v143, s[26:27] offset:3072
	global_load_ushort v7, v143, s[26:27] offset:3584
	s_add_u32 s26, s26, 0x1000
	s_addc_u32 s27, s27, 0
	global_load_ushort v8, v143, s[26:27]
	global_load_ushort v9, v143, s[26:27] offset:512
	global_load_ushort v10, v143, s[26:27] offset:1024
	global_load_ushort v11, v143, s[26:27] offset:1536
	global_load_ushort v12, v143, s[26:27] offset:2048
	global_load_ushort v13, v143, s[26:27] offset:2560
	global_load_ushort v14, v143, s[26:27] offset:3072
	global_load_ushort v15, v143, s[26:27] offset:3584
	v_mov_b32_e32 v145, 0
	s_waitcnt vmcnt(32)
	ds_write_b128 v147, v[44:47]
	s_waitcnt lgkmcnt(0)
	ds_read_b128 v[16:19], v139 offset:0
	ds_read_b128 v[20:23], v139 offset:16
	ds_read_b128 v[24:27], v139 offset:32
	ds_read_b128 v[28:31], v139 offset:48
	ds_read_b128 v[176:179], v139 offset:64
	ds_read_b128 v[180:183], v139 offset:80
	ds_read_b128 v[184:187], v139 offset:96
	ds_read_b128 v[188:191], v139 offset:112
	ds_read_b128 v[192:195], v139 offset:128
	ds_read_b128 v[196:199], v139 offset:144
	ds_read_b128 v[200:203], v139 offset:160
	ds_read_b128 v[206:209], v139 offset:176
	s_waitcnt lgkmcnt(8)
	v_mov_b32_e32 v32, v138
	v_fmac_f32_e32 v32, v16, v210
	v_fmac_f32_e32 v32, v17, v211
	v_fmac_f32_e32 v32, v18, v212
	v_fmac_f32_e32 v32, v19, v213
	v_fmac_f32_e32 v32, v20, v214
	v_fmac_f32_e32 v32, v21, v215
	v_fmac_f32_e32 v32, v22, v216
	v_fmac_f32_e32 v32, v23, v217
	v_fmac_f32_e32 v32, v24, v218
	v_fmac_f32_e32 v32, v25, v219
	v_fmac_f32_e32 v32, v26, v220
	v_fmac_f32_e32 v32, v27, v221
	v_fmac_f32_e32 v32, v28, v128
	v_fmac_f32_e32 v32, v29, v129
	v_fmac_f32_e32 v32, v30, v130
	v_fmac_f32_e32 v32, v31, v131
	ds_read_b128 v[16:19], v139 offset:192
	ds_read_b128 v[20:23], v139 offset:208
	ds_read_b128 v[24:27], v139 offset:224
	ds_read_b128 v[28:31], v139 offset:240
	v_min_f32_e32 v33, 0, v32
	v_mul_f32_e64 v34, |v32|, s11
	v_exp_f32_e32 v34, v34
	s_nop 0
	v_add_f32_e32 v34, 1.0, v34
	v_log_f32_e32 v34, v34
	s_nop 0
	v_mul_f32_e32 v34, s12, v34
	v_sub_f32_e32 v33, v33, v34
	v_mul_f32_e32 v112, s13, v33
	v_add_f32_e32 v145, v145, v112
	s_waitcnt lgkmcnt(8)
	v_mov_b32_e32 v32, v138
	v_fmac_f32_e32 v32, v176, v210
	v_fmac_f32_e32 v32, v177, v211
	v_fmac_f32_e32 v32, v178, v212
	v_fmac_f32_e32 v32, v179, v213
	v_fmac_f32_e32 v32, v180, v214
	v_fmac_f32_e32 v32, v181, v215
	v_fmac_f32_e32 v32, v182, v216
	v_fmac_f32_e32 v32, v183, v217
	v_fmac_f32_e32 v32, v184, v218
	v_fmac_f32_e32 v32, v185, v219
	v_fmac_f32_e32 v32, v186, v220
	v_fmac_f32_e32 v32, v187, v221
	v_fmac_f32_e32 v32, v188, v128
	v_fmac_f32_e32 v32, v189, v129
	v_fmac_f32_e32 v32, v190, v130
	v_fmac_f32_e32 v32, v191, v131
	ds_read_b128 v[176:179], v139 offset:256
	ds_read_b128 v[180:183], v139 offset:272
	ds_read_b128 v[184:187], v139 offset:288
	ds_read_b128 v[188:191], v139 offset:304
	v_min_f32_e32 v33, 0, v32
	v_mul_f32_e64 v34, |v32|, s11
	v_exp_f32_e32 v34, v34
	s_nop 0
	v_add_f32_e32 v34, 1.0, v34
	v_log_f32_e32 v34, v34
	s_nop 0
	v_mul_f32_e32 v34, s12, v34
	v_sub_f32_e32 v33, v33, v34
	v_mul_f32_e32 v113, s13, v33
	v_add_f32_e32 v145, v145, v113
	s_waitcnt lgkmcnt(8)
	v_mov_b32_e32 v32, v138
	v_fmac_f32_e32 v32, v192, v210
	v_fmac_f32_e32 v32, v193, v211
	v_fmac_f32_e32 v32, v194, v212
	v_fmac_f32_e32 v32, v195, v213
	v_fmac_f32_e32 v32, v196, v214
	v_fmac_f32_e32 v32, v197, v215
	v_fmac_f32_e32 v32, v198, v216
	v_fmac_f32_e32 v32, v199, v217
	v_fmac_f32_e32 v32, v200, v218
	v_fmac_f32_e32 v32, v201, v219
	v_fmac_f32_e32 v32, v202, v220
	v_fmac_f32_e32 v32, v203, v221
	v_fmac_f32_e32 v32, v206, v128
	v_fmac_f32_e32 v32, v207, v129
	v_fmac_f32_e32 v32, v208, v130
	v_fmac_f32_e32 v32, v209, v131
	ds_read_b128 v[192:195], v139 offset:320
	ds_read_b128 v[196:199], v139 offset:336
	ds_read_b128 v[200:203], v139 offset:352
	ds_read_b128 v[206:209], v139 offset:368
	v_min_f32_e32 v33, 0, v32
	v_mul_f32_e64 v34, |v32|, s11
	v_exp_f32_e32 v34, v34
	s_nop 0
	v_add_f32_e32 v34, 1.0, v34
	v_log_f32_e32 v34, v34
	s_nop 0
	v_mul_f32_e32 v34, s12, v34
	v_sub_f32_e32 v33, v33, v34
	v_mul_f32_e32 v114, s13, v33
	v_add_f32_e32 v145, v145, v114
	s_waitcnt lgkmcnt(8)
	v_mov_b32_e32 v32, v138
	v_fmac_f32_e32 v32, v16, v210
	v_fmac_f32_e32 v32, v17, v211
	v_fmac_f32_e32 v32, v18, v212
	v_fmac_f32_e32 v32, v19, v213
	v_fmac_f32_e32 v32, v20, v214
	v_fmac_f32_e32 v32, v21, v215
	v_fmac_f32_e32 v32, v22, v216
	v_fmac_f32_e32 v32, v23, v217
	v_fmac_f32_e32 v32, v24, v218
	v_fmac_f32_e32 v32, v25, v219
	v_fmac_f32_e32 v32, v26, v220
	v_fmac_f32_e32 v32, v27, v221
	v_fmac_f32_e32 v32, v28, v128
	v_fmac_f32_e32 v32, v29, v129
	v_fmac_f32_e32 v32, v30, v130
	v_fmac_f32_e32 v32, v31, v131
	ds_read_b128 v[16:19], v139 offset:384
	ds_read_b128 v[20:23], v139 offset:400
	ds_read_b128 v[24:27], v139 offset:416
	ds_read_b128 v[28:31], v139 offset:432
	v_min_f32_e32 v33, 0, v32
	v_mul_f32_e64 v34, |v32|, s11
	v_exp_f32_e32 v34, v34
	s_nop 0
	v_add_f32_e32 v34, 1.0, v34
	v_log_f32_e32 v34, v34
	s_nop 0
	v_mul_f32_e32 v34, s12, v34
	v_sub_f32_e32 v33, v33, v34
	v_mul_f32_e32 v115, s13, v33
	v_add_f32_e32 v145, v145, v115
	s_waitcnt lgkmcnt(8)
	v_mov_b32_e32 v32, v138
	v_fmac_f32_e32 v32, v176, v210
	v_fmac_f32_e32 v32, v177, v211
	v_fmac_f32_e32 v32, v178, v212
	v_fmac_f32_e32 v32, v179, v213
	v_fmac_f32_e32 v32, v180, v214
	v_fmac_f32_e32 v32, v181, v215
	v_fmac_f32_e32 v32, v182, v216
	v_fmac_f32_e32 v32, v183, v217
	v_fmac_f32_e32 v32, v184, v218
	v_fmac_f32_e32 v32, v185, v219
	v_fmac_f32_e32 v32, v186, v220
	v_fmac_f32_e32 v32, v187, v221
	v_fmac_f32_e32 v32, v188, v128
	v_fmac_f32_e32 v32, v189, v129
	v_fmac_f32_e32 v32, v190, v130
	v_fmac_f32_e32 v32, v191, v131
	ds_read_b128 v[176:179], v139 offset:448
	ds_read_b128 v[180:183], v139 offset:464
	ds_read_b128 v[184:187], v139 offset:480
	ds_read_b128 v[188:191], v139 offset:496
	v_min_f32_e32 v33, 0, v32
	v_mul_f32_e64 v34, |v32|, s11
	v_exp_f32_e32 v34, v34
	s_nop 0
	v_add_f32_e32 v34, 1.0, v34
	v_log_f32_e32 v34, v34
	s_nop 0
	v_mul_f32_e32 v34, s12, v34
	v_sub_f32_e32 v33, v33, v34
	v_mul_f32_e32 v116, s13, v33
	v_add_f32_e32 v145, v145, v116
	s_waitcnt lgkmcnt(8)
	v_mov_b32_e32 v32, v138
	v_fmac_f32_e32 v32, v192, v210
	v_fmac_f32_e32 v32, v193, v211
	v_fmac_f32_e32 v32, v194, v212
	v_fmac_f32_e32 v32, v195, v213
	v_fmac_f32_e32 v32, v196, v214
	v_fmac_f32_e32 v32, v197, v215
	v_fmac_f32_e32 v32, v198, v216
	v_fmac_f32_e32 v32, v199, v217
	v_fmac_f32_e32 v32, v200, v218
	v_fmac_f32_e32 v32, v201, v219
	v_fmac_f32_e32 v32, v202, v220
	v_fmac_f32_e32 v32, v203, v221
	v_fmac_f32_e32 v32, v206, v128
	v_fmac_f32_e32 v32, v207, v129
	v_fmac_f32_e32 v32, v208, v130
	v_fmac_f32_e32 v32, v209, v131
	ds_read_b128 v[192:195], v139 offset:512
	ds_read_b128 v[196:199], v139 offset:528
	ds_read_b128 v[200:203], v139 offset:544
	ds_read_b128 v[206:209], v139 offset:560
	v_min_f32_e32 v33, 0, v32
	v_mul_f32_e64 v34, |v32|, s11
	v_exp_f32_e32 v34, v34
	s_nop 0
	v_add_f32_e32 v34, 1.0, v34
	v_log_f32_e32 v34, v34
	s_nop 0
	v_mul_f32_e32 v34, s12, v34
	v_sub_f32_e32 v33, v33, v34
	v_mul_f32_e32 v117, s13, v33
	v_add_f32_e32 v145, v145, v117
	s_waitcnt lgkmcnt(8)
	v_mov_b32_e32 v32, v138
	v_fmac_f32_e32 v32, v16, v210
	v_fmac_f32_e32 v32, v17, v211
	v_fmac_f32_e32 v32, v18, v212
	v_fmac_f32_e32 v32, v19, v213
	v_fmac_f32_e32 v32, v20, v214
	v_fmac_f32_e32 v32, v21, v215
	v_fmac_f32_e32 v32, v22, v216
	v_fmac_f32_e32 v32, v23, v217
	v_fmac_f32_e32 v32, v24, v218
	v_fmac_f32_e32 v32, v25, v219
	v_fmac_f32_e32 v32, v26, v220
	v_fmac_f32_e32 v32, v27, v221
	v_fmac_f32_e32 v32, v28, v128
	v_fmac_f32_e32 v32, v29, v129
	v_fmac_f32_e32 v32, v30, v130
	v_fmac_f32_e32 v32, v31, v131
	ds_read_b128 v[16:19], v139 offset:576
	ds_read_b128 v[20:23], v139 offset:592
	ds_read_b128 v[24:27], v139 offset:608
	ds_read_b128 v[28:31], v139 offset:624
	v_min_f32_e32 v33, 0, v32
	v_mul_f32_e64 v34, |v32|, s11
	v_exp_f32_e32 v34, v34
	s_nop 0
	v_add_f32_e32 v34, 1.0, v34
	v_log_f32_e32 v34, v34
	s_nop 0
	v_mul_f32_e32 v34, s12, v34
	v_sub_f32_e32 v33, v33, v34
	v_mul_f32_e32 v118, s13, v33
	v_add_f32_e32 v145, v145, v118
	s_waitcnt lgkmcnt(8)
	v_mov_b32_e32 v32, v138
	v_fmac_f32_e32 v32, v176, v210
	v_fmac_f32_e32 v32, v177, v211
	v_fmac_f32_e32 v32, v178, v212
	v_fmac_f32_e32 v32, v179, v213
	v_fmac_f32_e32 v32, v180, v214
	v_fmac_f32_e32 v32, v181, v215
	v_fmac_f32_e32 v32, v182, v216
	v_fmac_f32_e32 v32, v183, v217
	v_fmac_f32_e32 v32, v184, v218
	v_fmac_f32_e32 v32, v185, v219
	v_fmac_f32_e32 v32, v186, v220
	v_fmac_f32_e32 v32, v187, v221
	v_fmac_f32_e32 v32, v188, v128
	v_fmac_f32_e32 v32, v189, v129
	v_fmac_f32_e32 v32, v190, v130
	v_fmac_f32_e32 v32, v191, v131
	ds_read_b128 v[176:179], v139 offset:640
	ds_read_b128 v[180:183], v139 offset:656
	ds_read_b128 v[184:187], v139 offset:672
	ds_read_b128 v[188:191], v139 offset:688
	v_min_f32_e32 v33, 0, v32
	v_mul_f32_e64 v34, |v32|, s11
	v_exp_f32_e32 v34, v34
	s_nop 0
	v_add_f32_e32 v34, 1.0, v34
	v_log_f32_e32 v34, v34
	s_nop 0
	v_mul_f32_e32 v34, s12, v34
	v_sub_f32_e32 v33, v33, v34
	v_mul_f32_e32 v119, s13, v33
	v_add_f32_e32 v145, v145, v119
	s_waitcnt lgkmcnt(8)
	v_mov_b32_e32 v32, v138
	v_fmac_f32_e32 v32, v192, v210
	v_fmac_f32_e32 v32, v193, v211
	v_fmac_f32_e32 v32, v194, v212
	v_fmac_f32_e32 v32, v195, v213
	v_fmac_f32_e32 v32, v196, v214
	v_fmac_f32_e32 v32, v197, v215
	v_fmac_f32_e32 v32, v198, v216
	v_fmac_f32_e32 v32, v199, v217
	v_fmac_f32_e32 v32, v200, v218
	v_fmac_f32_e32 v32, v201, v219
	v_fmac_f32_e32 v32, v202, v220
	v_fmac_f32_e32 v32, v203, v221
	v_fmac_f32_e32 v32, v206, v128
	v_fmac_f32_e32 v32, v207, v129
	v_fmac_f32_e32 v32, v208, v130
	v_fmac_f32_e32 v32, v209, v131
	ds_read_b128 v[192:195], v139 offset:704
	ds_read_b128 v[196:199], v139 offset:720
	ds_read_b128 v[200:203], v139 offset:736
	ds_read_b128 v[206:209], v139 offset:752
	v_min_f32_e32 v33, 0, v32
	v_mul_f32_e64 v34, |v32|, s11
	v_exp_f32_e32 v34, v34
	s_nop 0
	v_add_f32_e32 v34, 1.0, v34
	v_log_f32_e32 v34, v34
	s_nop 0
	v_mul_f32_e32 v34, s12, v34
	v_sub_f32_e32 v33, v33, v34
	v_mul_f32_e32 v120, s13, v33
	v_add_f32_e32 v145, v145, v120
	s_waitcnt lgkmcnt(8)
	v_mov_b32_e32 v32, v138
	v_fmac_f32_e32 v32, v16, v210
	v_fmac_f32_e32 v32, v17, v211
	v_fmac_f32_e32 v32, v18, v212
	v_fmac_f32_e32 v32, v19, v213
	v_fmac_f32_e32 v32, v20, v214
	v_fmac_f32_e32 v32, v21, v215
	v_fmac_f32_e32 v32, v22, v216
	v_fmac_f32_e32 v32, v23, v217
	v_fmac_f32_e32 v32, v24, v218
	v_fmac_f32_e32 v32, v25, v219
	v_fmac_f32_e32 v32, v26, v220
	v_fmac_f32_e32 v32, v27, v221
	v_fmac_f32_e32 v32, v28, v128
	v_fmac_f32_e32 v32, v29, v129
	v_fmac_f32_e32 v32, v30, v130
	v_fmac_f32_e32 v32, v31, v131
	ds_read_b128 v[16:19], v139 offset:768
	ds_read_b128 v[20:23], v139 offset:784
	ds_read_b128 v[24:27], v139 offset:800
	ds_read_b128 v[28:31], v139 offset:816
	v_min_f32_e32 v33, 0, v32
	v_mul_f32_e64 v34, |v32|, s11
	v_exp_f32_e32 v34, v34
	s_nop 0
	v_add_f32_e32 v34, 1.0, v34
	v_log_f32_e32 v34, v34
	s_nop 0
	v_mul_f32_e32 v34, s12, v34
	v_sub_f32_e32 v33, v33, v34
	v_mul_f32_e32 v121, s13, v33
	v_add_f32_e32 v145, v145, v121
	s_waitcnt lgkmcnt(8)
	v_mov_b32_e32 v32, v138
	v_fmac_f32_e32 v32, v176, v210
	v_fmac_f32_e32 v32, v177, v211
	v_fmac_f32_e32 v32, v178, v212
	v_fmac_f32_e32 v32, v179, v213
	v_fmac_f32_e32 v32, v180, v214
	v_fmac_f32_e32 v32, v181, v215
	v_fmac_f32_e32 v32, v182, v216
	v_fmac_f32_e32 v32, v183, v217
	v_fmac_f32_e32 v32, v184, v218
	v_fmac_f32_e32 v32, v185, v219
	v_fmac_f32_e32 v32, v186, v220
	v_fmac_f32_e32 v32, v187, v221
	v_fmac_f32_e32 v32, v188, v128
	v_fmac_f32_e32 v32, v189, v129
	v_fmac_f32_e32 v32, v190, v130
	v_fmac_f32_e32 v32, v191, v131
	ds_read_b128 v[176:179], v139 offset:832
	ds_read_b128 v[180:183], v139 offset:848
	ds_read_b128 v[184:187], v139 offset:864
	ds_read_b128 v[188:191], v139 offset:880
	v_min_f32_e32 v33, 0, v32
	v_mul_f32_e64 v34, |v32|, s11
	v_exp_f32_e32 v34, v34
	s_nop 0
	v_add_f32_e32 v34, 1.0, v34
	v_log_f32_e32 v34, v34
	s_nop 0
	v_mul_f32_e32 v34, s12, v34
	v_sub_f32_e32 v33, v33, v34
	v_mul_f32_e32 v122, s13, v33
	v_add_f32_e32 v145, v145, v122
	s_waitcnt lgkmcnt(8)
	v_mov_b32_e32 v32, v138
	v_fmac_f32_e32 v32, v192, v210
	v_fmac_f32_e32 v32, v193, v211
	v_fmac_f32_e32 v32, v194, v212
	v_fmac_f32_e32 v32, v195, v213
	v_fmac_f32_e32 v32, v196, v214
	v_fmac_f32_e32 v32, v197, v215
	v_fmac_f32_e32 v32, v198, v216
	v_fmac_f32_e32 v32, v199, v217
	v_fmac_f32_e32 v32, v200, v218
	v_fmac_f32_e32 v32, v201, v219
	v_fmac_f32_e32 v32, v202, v220
	v_fmac_f32_e32 v32, v203, v221
	v_fmac_f32_e32 v32, v206, v128
	v_fmac_f32_e32 v32, v207, v129
	v_fmac_f32_e32 v32, v208, v130
	v_fmac_f32_e32 v32, v209, v131
	ds_read_b128 v[192:195], v139 offset:896
	ds_read_b128 v[196:199], v139 offset:912
	ds_read_b128 v[200:203], v139 offset:928
	ds_read_b128 v[206:209], v139 offset:944
	v_min_f32_e32 v33, 0, v32
	v_mul_f32_e64 v34, |v32|, s11
	v_exp_f32_e32 v34, v34
	s_nop 0
	v_add_f32_e32 v34, 1.0, v34
	v_log_f32_e32 v34, v34
	s_nop 0
	v_mul_f32_e32 v34, s12, v34
	v_sub_f32_e32 v33, v33, v34
	v_mul_f32_e32 v123, s13, v33
	v_add_f32_e32 v145, v145, v123
	s_waitcnt lgkmcnt(8)
	v_mov_b32_e32 v32, v138
	v_fmac_f32_e32 v32, v16, v210
	v_fmac_f32_e32 v32, v17, v211
	v_fmac_f32_e32 v32, v18, v212
	v_fmac_f32_e32 v32, v19, v213
	v_fmac_f32_e32 v32, v20, v214
	v_fmac_f32_e32 v32, v21, v215
	v_fmac_f32_e32 v32, v22, v216
	v_fmac_f32_e32 v32, v23, v217
	v_fmac_f32_e32 v32, v24, v218
	v_fmac_f32_e32 v32, v25, v219
	v_fmac_f32_e32 v32, v26, v220
	v_fmac_f32_e32 v32, v27, v221
	v_fmac_f32_e32 v32, v28, v128
	v_fmac_f32_e32 v32, v29, v129
	v_fmac_f32_e32 v32, v30, v130
	v_fmac_f32_e32 v32, v31, v131
	ds_read_b128 v[16:19], v139 offset:960
	ds_read_b128 v[20:23], v139 offset:976
	ds_read_b128 v[24:27], v139 offset:992
	ds_read_b128 v[28:31], v139 offset:1008
	v_min_f32_e32 v33, 0, v32
	v_mul_f32_e64 v34, |v32|, s11
	v_exp_f32_e32 v34, v34
	s_nop 0
	v_add_f32_e32 v34, 1.0, v34
	v_log_f32_e32 v34, v34
	s_nop 0
	v_mul_f32_e32 v34, s12, v34
	v_sub_f32_e32 v33, v33, v34
	v_mul_f32_e32 v124, s13, v33
	v_add_f32_e32 v145, v145, v124
	s_waitcnt lgkmcnt(8)
	v_mov_b32_e32 v32, v138
	v_fmac_f32_e32 v32, v176, v210
	v_fmac_f32_e32 v32, v177, v211
	v_fmac_f32_e32 v32, v178, v212
	v_fmac_f32_e32 v32, v179, v213
	v_fmac_f32_e32 v32, v180, v214
	v_fmac_f32_e32 v32, v181, v215
	v_fmac_f32_e32 v32, v182, v216
	v_fmac_f32_e32 v32, v183, v217
	v_fmac_f32_e32 v32, v184, v218
	v_fmac_f32_e32 v32, v185, v219
	v_fmac_f32_e32 v32, v186, v220
	v_fmac_f32_e32 v32, v187, v221
	v_fmac_f32_e32 v32, v188, v128
	v_fmac_f32_e32 v32, v189, v129
	v_fmac_f32_e32 v32, v190, v130
	v_fmac_f32_e32 v32, v191, v131
	v_min_f32_e32 v33, 0, v32
	v_mul_f32_e64 v34, |v32|, s11
	v_exp_f32_e32 v34, v34
	s_nop 0
	v_add_f32_e32 v34, 1.0, v34
	v_log_f32_e32 v34, v34
	s_nop 0
	v_mul_f32_e32 v34, s12, v34
	v_sub_f32_e32 v33, v33, v34
	v_mul_f32_e32 v125, s13, v33
	v_add_f32_e32 v145, v145, v125
	s_waitcnt lgkmcnt(4)
	v_mov_b32_e32 v32, v138
	v_fmac_f32_e32 v32, v192, v210
	v_fmac_f32_e32 v32, v193, v211
	v_fmac_f32_e32 v32, v194, v212
	v_fmac_f32_e32 v32, v195, v213
	v_fmac_f32_e32 v32, v196, v214
	v_fmac_f32_e32 v32, v197, v215
	v_fmac_f32_e32 v32, v198, v216
	v_fmac_f32_e32 v32, v199, v217
	v_fmac_f32_e32 v32, v200, v218
	v_fmac_f32_e32 v32, v201, v219
	v_fmac_f32_e32 v32, v202, v220
	v_fmac_f32_e32 v32, v203, v221
	v_fmac_f32_e32 v32, v206, v128
	v_fmac_f32_e32 v32, v207, v129
	v_fmac_f32_e32 v32, v208, v130
	v_fmac_f32_e32 v32, v209, v131
	v_min_f32_e32 v33, 0, v32
	v_mul_f32_e64 v34, |v32|, s11
	v_exp_f32_e32 v34, v34
	s_nop 0
	v_add_f32_e32 v34, 1.0, v34
	v_log_f32_e32 v34, v34
	s_nop 0
	v_mul_f32_e32 v34, s12, v34
	v_sub_f32_e32 v33, v33, v34
	v_mul_f32_e32 v126, s13, v33
	v_add_f32_e32 v145, v145, v126
	s_waitcnt lgkmcnt(0)
	v_mov_b32_e32 v32, v138
	v_fmac_f32_e32 v32, v16, v210
	v_fmac_f32_e32 v32, v17, v211
	v_fmac_f32_e32 v32, v18, v212
	v_fmac_f32_e32 v32, v19, v213
	v_fmac_f32_e32 v32, v20, v214
	v_fmac_f32_e32 v32, v21, v215
	v_fmac_f32_e32 v32, v22, v216
	v_fmac_f32_e32 v32, v23, v217
	v_fmac_f32_e32 v32, v24, v218
	v_fmac_f32_e32 v32, v25, v219
	v_fmac_f32_e32 v32, v26, v220
	v_fmac_f32_e32 v32, v27, v221
	v_fmac_f32_e32 v32, v28, v128
	v_fmac_f32_e32 v32, v29, v129
	v_fmac_f32_e32 v32, v30, v130
	v_fmac_f32_e32 v32, v31, v131
	v_min_f32_e32 v33, 0, v32
	v_mul_f32_e64 v34, |v32|, s11
	v_exp_f32_e32 v34, v34
	s_nop 0
	v_add_f32_e32 v34, 1.0, v34
	v_log_f32_e32 v34, v34
	s_nop 0
	v_mul_f32_e32 v34, s12, v34
	v_sub_f32_e32 v33, v33, v34
	v_mul_f32_e32 v127, s13, v33
	v_add_f32_e32 v145, v145, v127

.Lpre_g_next:
.Lpre_next:
	s_add_i32 s16, s16, s96
	s_cmpk_lt_i32 s16, 0x2080
	s_cbranch_scc1 .Lpre_loop
	s_branch .LBB0_377
